# v39
# speedup vs baseline: 1.0068x; 1.0068x over previous
; #define WS_(p) opq_ws((p).ws)
;   unsigned* ctr = (unsigned*)(WS_(p) + OFF_CTR) + L * 32 + rep * 16;
;   unsigned* bc = (unsigned*)(smem + SHM_BYTES - 16);
;   const int qlen[8] = {132, 132, 132, 132, 132, 132, 132, 132};
;   for (;;) {
;     const int it = next_item(ctr, qlen, bc);
.LBB0_859:
	s_or_b64 exec, exec, s[36:37]
	s_lshl_b32 s50, s50, 5
	s_mov_b64 s[4:5], s[70:71]
	s_waitcnt lgkmcnt(0)
	s_barrier
	s_lshl_b64 s[0:1], s[50:51], 2
	s_add_u32 s4, s4, s0
	s_addc_u32 s5, s5, s1
	s_add_u32 s26, s4, 0x404000
	s_addc_u32 s27, s5, 0
	v_readlane_b32 s50, v254, 47
	v_readfirstlane_b32 s100, v178
	s_nop 3
	s_lshr_b32 s100, s100, 6
	s_cmp_ge_u32 s100, 4
	s_cbranch_scc0 .Lprio_skip
	s_setprio 2
.Lprio_skip:
	s_branch .LBB0_861
.LBB0_860:
	s_or_b64 exec, exec, s[8:9]
	s_waitcnt lgkmcnt(0)
	s_barrier

; DI unsigned xb_ld(unsigned* p)              { return __hip_atomic_load(p, __ATOMIC_RELAXED, __HIP_MEMORY_SCOPE_AGENT); }
; DI void xcd_barrier_complete(unsigned* bar, unsigned x, unsigned& nloc, unsigned& nx) {
;   const unsigned G = gridDim.x * gridDim.y * gridDim.z;
;   unsigned sum, cnt, mine, sp = 0u;
;   for (;;) {
;     sum = 0u; cnt = 0u; mine = 0u;
;     #pragma unroll
;     for (unsigned j = 0; j < 16; ++j) { const unsigned c = xb_ld(&bar[XB_XCNT(j)]); sum += c; cnt += (c > 0u) ? 1u : 0u; mine = (j == x) ? c : mine; }
; DI void xcd_barrier(const XcdBarrier& b) {
;   asm volatile("s_waitcnt vmcnt(0)" ::: "memory");
;   __syncthreads();
;   if (threadIdx.x == 0) {
;     unsigned* bar = b.bar;
;     __builtin_amdgcn_s_waitcnt(0);
;     unsigned nloc = b.st[0], nx = b.st[1];
;     if (nloc == 0u) { xcd_barrier_complete(bar, b.x, nloc, nx); b.st[0] = nloc; b.st[1] = nx; }
.LBB0_1682:
	s_setprio 0
	s_mov_b64 s[52:53], s[70:71]
	s_getreg_b32 s0, hwreg(HW_REG_XCC_ID, 0, 4)
	s_waitcnt vmcnt(0)
	s_barrier
	s_mov_b64 s[36:37], exec
	v_readlane_b32 s4, v254, 7
	v_readlane_b32 s5, v254, 8
	s_and_b64 s[4:5], s[36:37], s[4:5]
	s_mov_b64 exec, s[4:5]
	s_cbranch_execz .LBB0_1726
	v_readlane_b32 s1, v254, 61
	s_waitcnt vmcnt(0) expcnt(0) lgkmcnt(0)
	s_and_b32 s50, s0, 15
	v_mov_b32_e32 v0, s1
	ds_read_b32 v2, v0
	v_readlane_b32 s1, v254, 62
	s_waitcnt lgkmcnt(0)
	v_cmp_ne_u32_e32 vcc, 0, v2
	v_mov_b32_e32 v0, s1
	ds_read_b32 v0, v0
	s_cbranch_vccnz .LBB0_1697
	s_add_u32 s0, s52, 0x404600
	s_addc_u32 s1, s53, 0
	s_add_u32 s6, s52, 0x404800
	s_addc_u32 s7, s53, 0
	s_add_u32 s8, s52, 0x404900
	s_addc_u32 s9, s53, 0
	s_add_u32 s10, s52, 0x404a00
	s_addc_u32 s11, s53, 0
	s_add_u32 s12, s52, 0x404b00
	s_addc_u32 s13, s53, 0
	s_add_u32 s14, s52, 0x404c00
	s_addc_u32 s15, s53, 0
	s_add_u32 s16, s52, 0x404d00
	s_addc_u32 s17, s53, 0
	s_add_u32 s18, s52, 0x404e00
	s_addc_u32 s19, s53, 0
	s_add_u32 s24, s52, 0x404f00
	s_addc_u32 s25, s53, 0
	s_add_u32 s26, s52, 0x405000
	s_addc_u32 s27, s53, 0
	s_add_u32 s28, s52, 0x405100
	s_addc_u32 s29, s53, 0
	s_add_u32 s30, s52, 0x405200
	s_addc_u32 s31, s53, 0
	s_add_u32 s34, s52, 0x405300
	v_writelane_b32 v255, s36, 16
	s_addc_u32 s35, s53, 0
	s_mov_b32 s85, 1
	v_writelane_b32 v255, s37, 17
	s_add_u32 s36, s52, 0x405400
	s_addc_u32 s37, s53, 0
	s_add_u32 s38, s52, 0x405500
	s_addc_u32 s39, s53, 0
	s_add_u32 s68, s52, 0x405600
	s_addc_u32 s69, s53, 0
	s_add_u32 s72, s52, 0x405700
	s_addc_u32 s73, s53, 0
	s_mov_b64 s[80:81], 0
	s_branch .LBB0_1687
